# XCD-local barrier enable check also requires the grid to be a multiple of 64 (fixed GEMM row panel per workgroup)
# speedup vs baseline: 1.0023x; 1.0023x over previous
.LBB0_61:
	s_cmp_eq_u32 s17, 1
	s_cbranch_scc0 .Lbar_chk_done
	s_mov_b64 exec, 1
	v_readlane_b32 s4, v252, 4
	v_readlane_b32 s5, v252, 5
	v_mov_b32_e32 v3, 0x3400
	s_nop 3
	global_load_dwordx4 v[4:7], v3, s[4:5] sc1
	global_load_dwordx4 v[8:11], v3, s[4:5] offset:16 sc1
	s_mov_b32 s10, 0
	s_mov_b32 s11, 1
	s_waitcnt vmcnt(0)
	v_readfirstlane_b32 s6, v4
	s_bcnt1_i32_b32 s7, s6
	s_cmp_eq_u32 s7, 1
	s_cselect_b32 s11, s11, 0
	s_or_b32 s10, s10, s6
	v_readfirstlane_b32 s6, v5
	s_bcnt1_i32_b32 s7, s6
	s_cmp_eq_u32 s7, 1
	s_cselect_b32 s11, s11, 0
	s_or_b32 s10, s10, s6
	v_readfirstlane_b32 s6, v6
	s_bcnt1_i32_b32 s7, s6
	s_cmp_eq_u32 s7, 1
	s_cselect_b32 s11, s11, 0
	s_or_b32 s10, s10, s6
	v_readfirstlane_b32 s6, v7
	s_bcnt1_i32_b32 s7, s6
	s_cmp_eq_u32 s7, 1
	s_cselect_b32 s11, s11, 0
	s_or_b32 s10, s10, s6
	v_readfirstlane_b32 s6, v8
	s_bcnt1_i32_b32 s7, s6
	s_cmp_eq_u32 s7, 1
	s_cselect_b32 s11, s11, 0
	s_or_b32 s10, s10, s6
	v_readfirstlane_b32 s6, v9
	s_bcnt1_i32_b32 s7, s6
	s_cmp_eq_u32 s7, 1
	s_cselect_b32 s11, s11, 0
	s_or_b32 s10, s10, s6
	v_readfirstlane_b32 s6, v10
	s_bcnt1_i32_b32 s7, s6
	s_cmp_eq_u32 s7, 1
	s_cselect_b32 s11, s11, 0
	s_or_b32 s10, s10, s6
	v_readfirstlane_b32 s6, v11
	s_bcnt1_i32_b32 s7, s6
	s_cmp_eq_u32 s7, 1
	s_cselect_b32 s11, s11, 0
	s_or_b32 s10, s10, s6
	s_bcnt1_i32_b32 s7, s10
	s_cmp_eq_u32 s7, 8
	s_cselect_b32 s11, s11, 0
	v_readlane_b32 s6, v252, 2
	v_readlane_b32 s7, v252, 3
	s_load_dword s6, s[6:7], 0x0
	s_waitcnt lgkmcnt(0)
	s_and_b32 s6, s6, 63
	s_cmp_eq_u32 s6, 0
	s_cselect_b32 s11, s11, 0
	s_nop 0
	v_writelane_b32 v255, s11, 40
